# peeled first K-tile of UP/DOWN units: the two counted DMA waits allow for the epilogue's 20/40 guaranteed in-flight stores (vmcnt 8 -> 28/48), same DMA guarantee under in-order vmcnt
# baseline (speedup 1.0000x reference)
; #define PG8_STAGE(bufoff, gbase, voff) do { _Pragma("unroll") for (int _i = 0; _i < 2; ++_i) \
;         __builtin_amdgcn_global_load_lds((const unsigned*)((const char*)(gbase) + (voff)[_i]), (PG8_LAS unsigned*)(lds + (bufoff) + ldsw + _i * 8192), 16, 0, 0); } while (0)
; #define PG8_LDA(dst, b, h) do { _Pragma("unroll") for (int m = 0; m < 4; ++m) _Pragma("unroll") for (int k = 0; k < 2; ++k) dst[m][k] = *(const PG8_LAS bf16x8*)(lds + PG8_SA(b, h) + aoff + m * 2048 + k * 1024); } while (0)
; #define PG8_LDB(dst, b, h) do { _Pragma("unroll") for (int n = 0; n < 2; ++n) _Pragma("unroll") for (int k = 0; k < 2; ++k) dst[n][k] = *(const PG8_LAS bf16x8*)(lds + PG8_SB(b, h) + boff + n * 2048 + k * 1024); } while (0)
; #define PG8_MMA(ai, bj, At, Bt) do { __builtin_amdgcn_s_setprio(1); _Pragma("unroll") for (int m = 0; m < 4; ++m) _Pragma("unroll") for (int n = 0; n < 2; ++n) _Pragma("unroll") for (int k = 0; k < 2; ++k) \
;         acc[ai][bj][m][n] = __builtin_amdgcn_mfma_f32_16x16x32_bf16(Bt[n][k], At[m][k], acc[ai][bj][m][n], 0, 0, 0); __builtin_amdgcn_s_setprio(0); } while (0)
; #define PG8_WAIT_V(n) asm volatile("s_waitcnt vmcnt(" #n ")" ::: "memory")
; #define PG8_WAIT_L(n) asm volatile("s_waitcnt lgkmcnt(" #n ")" ::: "memory")
; #define PG8_BAR __builtin_amdgcn_s_barrier()
; #define PG8_SCHED __builtin_amdgcn_sched_barrier(0)
;     ...
;             PG8_LDB(B0, 0, 0); PG8_LDB(B1, 0, 1); PG8_SCHED; PG8_LDA(At, 0, 0); PG8_STAGE(PG8_SA(1, 1), a1 + hstepA, voffA);
;             PG8_WAIT_V(8); PG8_WAIT_L(0); PG8_BAR; PG8_MMA(0, 0, At, B0); PG8_MMA(0, 1, At, B1); PG8_BAR; PG8_SCHED;
;             PG8_LDA(At, 0, 1); PG8_STAGE(PG8_SB(0, 0), b2, voffB); PG8_STAGE(PG8_SB(0, 1), b2 + hstepB, voffB); PG8_STAGE(PG8_SA(0, 0), a2, voffA);
;             PG8_WAIT_V(8); PG8_WAIT_L(0); PG8_BAR; PG8_MMA(1, 0, At, B0); PG8_MMA(1, 1, At, B1); PG8_BAR; PG8_SCHED;
.Lup_nostg:
	s_add_u32 s36, s34, 0x10000
	s_addc_u32 s37, s35, 0
	s_cmp_eq_u32 s66, 28
	s_cselect_b32 s88, s57, s36
	s_cselect_b32 s89, s27, s37
	s_cselect_b32 s86, vcc_lo, vcc_hi
	s_cselect_b32 s87, s25, s65
	s_add_u32 s46, s88, 0x8000
	s_addc_u32 s47, s89, 0
	s_add_i32 s96, 0, 0x10000
	v_add_u32_e32 v0, s96, v192
	s_add_i32 s97, 0, 0x14000
	ds_read_b128 v[130:133], v0
	ds_read_b128 v[134:137], v0 offset:1024
	ds_read_b128 v[138:141], v0 offset:2048
	ds_read_b128 v[142:145], v0 offset:3072
	v_add_u32_e32 v0, s97, v192
	ds_read_b128 v[146:149], v0
	ds_read_b128 v[150:153], v0 offset:1024
	ds_read_b128 v[154:157], v0 offset:2048
	ds_read_b128 v[170:173], v0 offset:3072
	s_add_i32 m0, s48, 0xc000
	ds_read_b128 v[174:177], v193
	ds_read_b128 v[178:181], v193 offset:1024
	ds_read_b128 v[182:185], v193 offset:2048
	ds_read_b128 v[186:189], v193 offset:3072
	ds_read_b128 v[194:197], v193 offset:4096
	ds_read_b128 v[198:201], v193 offset:5120
	ds_read_b128 v[202:205], v193 offset:6144
	ds_read_b128 v[206:209], v193 offset:7168
	global_load_lds_dwordx4 v166, s[34:35]
	s_add_i32 m0, s48, 0xe000
	s_nop 0
	global_load_lds_dwordx4 v168, s[34:35]
	s_waitcnt vmcnt(28)
	s_waitcnt lgkmcnt(0)
	s_barrier
	s_setprio 1
	s_waitcnt lgkmcnt(0)
	v_mfma_f32_16x16x32_bf16 v[126:129], v[130:133], v[174:177], 0
	v_mfma_f32_16x16x32_bf16 v[126:129], v[134:137], v[178:181], v[126:129]
	v_mfma_f32_16x16x32_bf16 v[122:125], v[142:145], v[178:181], 0
	v_mfma_f32_16x16x32_bf16 v[122:125], v[138:141], v[174:177], v[122:125]
	v_mfma_f32_16x16x32_bf16 v[114:117], v[138:141], v[182:185], 0
	v_mfma_f32_16x16x32_bf16 v[114:117], v[142:145], v[186:189], v[114:117]
	v_mfma_f32_16x16x32_bf16 v[118:121], v[134:137], v[186:189], 0
	v_mfma_f32_16x16x32_bf16 v[118:121], v[130:133], v[182:185], v[118:121]
	v_mfma_f32_16x16x32_bf16 v[110:113], v[130:133], v[194:197], 0
	v_mfma_f32_16x16x32_bf16 v[110:113], v[134:137], v[198:201], v[110:113]
	v_mfma_f32_16x16x32_bf16 v[106:109], v[142:145], v[198:201], 0
	v_mfma_f32_16x16x32_bf16 v[106:109], v[138:141], v[194:197], v[106:109]
	v_mfma_f32_16x16x32_bf16 v[98:101], v[138:141], v[202:205], 0
	v_mfma_f32_16x16x32_bf16 v[98:101], v[142:145], v[206:209], v[98:101]
	v_mfma_f32_16x16x32_bf16 v[102:105], v[134:137], v[206:209], 0
	v_mfma_f32_16x16x32_bf16 v[102:105], v[130:133], v[202:205], v[102:105]
	s_setprio 0
	s_setprio 1
	v_mfma_f32_16x16x32_bf16 v[30:33], v[146:149], v[174:177], 0
	v_mfma_f32_16x16x32_bf16 v[30:33], v[150:153], v[178:181], v[30:33]
	v_mfma_f32_16x16x32_bf16 v[46:49], v[170:173], v[178:181], 0
	v_mfma_f32_16x16x32_bf16 v[46:49], v[154:157], v[174:177], v[46:49]
	v_mfma_f32_16x16x32_bf16 v[34:37], v[154:157], v[182:185], 0
	v_mfma_f32_16x16x32_bf16 v[34:37], v[170:173], v[186:189], v[34:37]
	v_mfma_f32_16x16x32_bf16 v[26:29], v[150:153], v[186:189], 0
	v_mfma_f32_16x16x32_bf16 v[26:29], v[146:149], v[182:185], v[26:29]
	v_mfma_f32_16x16x32_bf16 v[94:97], v[146:149], v[194:197], 0
	v_mfma_f32_16x16x32_bf16 v[94:97], v[150:153], v[198:201], v[94:97]
	v_mfma_f32_16x16x32_bf16 v[90:93], v[170:173], v[198:201], 0
	v_mfma_f32_16x16x32_bf16 v[90:93], v[154:157], v[194:197], v[90:93]
	v_mfma_f32_16x16x32_bf16 v[82:85], v[154:157], v[202:205], 0
	v_mfma_f32_16x16x32_bf16 v[82:85], v[170:173], v[206:209], v[82:85]
	v_mfma_f32_16x16x32_bf16 v[86:89], v[150:153], v[206:209], 0
	v_mfma_f32_16x16x32_bf16 v[86:89], v[146:149], v[202:205], v[86:89]
	s_setprio 0
	s_barrier
	s_add_i32 s34, s96, s44
	s_mov_b32 m0, s34
	ds_read_b128 v[174:177], v193 offset:16384
	ds_read_b128 v[178:181], v193 offset:17408
	ds_read_b128 v[182:185], v193 offset:18432
	ds_read_b128 v[186:189], v193 offset:19456
	ds_read_b128 v[194:197], v193 offset:20480
	ds_read_b128 v[198:201], v193 offset:21504
	ds_read_b128 v[202:205], v193 offset:22528
	ds_read_b128 v[206:209], v193 offset:23552
	global_load_lds_dwordx4 v162, s[86:87]
	s_add_i32 m0, s34, 0x2000
	s_add_u32 s34, s86, 0x4000
	s_addc_u32 s35, s87, 0
	s_add_i32 s96, s97, s44
	global_load_lds_dwordx4 v158, s[86:87]
	s_mov_b32 m0, s96
	v_lshl_add_u64 v[210:211], s[88:89], 0, v[160:161]
	global_load_lds_dwordx4 v162, s[34:35]
	s_add_i32 m0, s96, 0x2000
	s_nop 0
	global_load_lds_dwordx4 v158, s[34:35]
	v_lshl_add_u64 v[190:191], s[88:89], 0, v[164:165]
	s_mov_b32 m0, s48
	s_nop 0
	global_load_lds_dwordx4 v[190:191], off
	s_mov_b32 m0, s49
	s_nop 0
	global_load_lds_dwordx4 v[210:211], off
	s_waitcnt vmcnt(28)
	s_waitcnt lgkmcnt(0)
	s_barrier
	s_setprio 1
	s_waitcnt lgkmcnt(0)
	v_mfma_f32_16x16x32_bf16 v[78:81], v[130:133], v[174:177], 0
	v_mfma_f32_16x16x32_bf16 v[78:81], v[134:137], v[178:181], v[78:81]
	v_mfma_f32_16x16x32_bf16 v[74:77], v[142:145], v[178:181], 0
	v_mfma_f32_16x16x32_bf16 v[74:77], v[138:141], v[174:177], v[74:77]
	v_mfma_f32_16x16x32_bf16 v[66:69], v[138:141], v[182:185], 0
	v_mfma_f32_16x16x32_bf16 v[66:69], v[142:145], v[186:189], v[66:69]
	v_mfma_f32_16x16x32_bf16 v[70:73], v[134:137], v[186:189], 0
	v_mfma_f32_16x16x32_bf16 v[70:73], v[130:133], v[182:185], v[70:73]
	v_mfma_f32_16x16x32_bf16 v[42:45], v[130:133], v[194:197], 0
	v_mfma_f32_16x16x32_bf16 v[42:45], v[134:137], v[198:201], v[42:45]
	v_mfma_f32_16x16x32_bf16 v[6:9], v[142:145], v[198:201], 0
	v_mfma_f32_16x16x32_bf16 v[6:9], v[138:141], v[194:197], v[6:9]
	v_mfma_f32_16x16x32_bf16 v[2:5], v[138:141], v[202:205], 0
	v_mfma_f32_16x16x32_bf16 v[2:5], v[142:145], v[206:209], v[2:5]
	v_mfma_f32_16x16x32_bf16 v[38:41], v[134:137], v[206:209], 0
	v_mfma_f32_16x16x32_bf16 v[38:41], v[130:133], v[202:205], v[38:41]
	s_setprio 0
	s_setprio 1
	v_mfma_f32_16x16x32_bf16 v[62:65], v[146:149], v[174:177], 0
	v_mfma_f32_16x16x32_bf16 v[62:65], v[150:153], v[178:181], v[62:65]
	v_mfma_f32_16x16x32_bf16 v[58:61], v[170:173], v[178:181], 0
	v_mfma_f32_16x16x32_bf16 v[58:61], v[154:157], v[174:177], v[58:61]
	v_mfma_f32_16x16x32_bf16 v[50:53], v[154:157], v[182:185], 0
	v_mfma_f32_16x16x32_bf16 v[50:53], v[170:173], v[186:189], v[50:53]
	v_mfma_f32_16x16x32_bf16 v[54:57], v[150:153], v[186:189], 0
	v_mfma_f32_16x16x32_bf16 v[54:57], v[146:149], v[182:185], v[54:57]
	v_mfma_f32_16x16x32_bf16 v[22:25], v[146:149], v[194:197], 0
	v_mfma_f32_16x16x32_bf16 v[22:25], v[150:153], v[198:201], v[22:25]
	v_mfma_f32_16x16x32_bf16 v[18:21], v[170:173], v[198:201], 0
	v_mfma_f32_16x16x32_bf16 v[18:21], v[154:157], v[194:197], v[18:21]
	v_mfma_f32_16x16x32_bf16 v[10:13], v[154:157], v[202:205], 0
	v_mfma_f32_16x16x32_bf16 v[10:13], v[170:173], v[206:209], v[10:13]
	v_mfma_f32_16x16x32_bf16 v[14:17], v[150:153], v[206:209], 0
	v_mfma_f32_16x16x32_bf16 v[14:17], v[146:149], v[202:205], v[14:17]
	s_setprio 0
	s_barrier
	s_branch .Lup_mid

; #define PG8_STAGE(bufoff, gbase, voff) do { _Pragma("unroll") for (int _i = 0; _i < 2; ++_i) \
;         __builtin_amdgcn_global_load_lds((const unsigned*)((const char*)(gbase) + (voff)[_i]), (PG8_LAS unsigned*)(lds + (bufoff) + ldsw + _i * 8192), 16, 0, 0); } while (0)
; #define PG8_LDA(dst, b, h) do { _Pragma("unroll") for (int m = 0; m < 4; ++m) _Pragma("unroll") for (int k = 0; k < 2; ++k) dst[m][k] = *(const PG8_LAS bf16x8*)(lds + PG8_SA(b, h) + aoff + m * 2048 + k * 1024); } while (0)
; #define PG8_LDB(dst, b, h) do { _Pragma("unroll") for (int n = 0; n < 2; ++n) _Pragma("unroll") for (int k = 0; k < 2; ++k) dst[n][k] = *(const PG8_LAS bf16x8*)(lds + PG8_SB(b, h) + boff + n * 2048 + k * 1024); } while (0)
; #define PG8_MMA(ai, bj, At, Bt) do { __builtin_amdgcn_s_setprio(1); _Pragma("unroll") for (int m = 0; m < 4; ++m) _Pragma("unroll") for (int n = 0; n < 2; ++n) _Pragma("unroll") for (int k = 0; k < 2; ++k) \
;         acc[ai][bj][m][n] = __builtin_amdgcn_mfma_f32_16x16x32_bf16(Bt[n][k], At[m][k], acc[ai][bj][m][n], 0, 0, 0); __builtin_amdgcn_s_setprio(0); } while (0)
; #define PG8_WAIT_V(n) asm volatile("s_waitcnt vmcnt(" #n ")" ::: "memory")
; #define PG8_WAIT_L(n) asm volatile("s_waitcnt lgkmcnt(" #n ")" ::: "memory")
; #define PG8_BAR __builtin_amdgcn_s_barrier()
; #define PG8_SCHED __builtin_amdgcn_sched_barrier(0)
;     ...
;             PG8_LDB(B0, 0, 0); PG8_LDB(B1, 0, 1); PG8_SCHED; PG8_LDA(At, 0, 0); PG8_STAGE(PG8_SA(1, 1), a1 + hstepA, voffA);
;             PG8_WAIT_V(8); PG8_WAIT_L(0); PG8_BAR; PG8_MMA(0, 0, At, B0); PG8_MMA(0, 1, At, B1); PG8_BAR; PG8_SCHED;
;             PG8_LDA(At, 0, 1); PG8_STAGE(PG8_SB(0, 0), b2, voffB); PG8_STAGE(PG8_SB(0, 1), b2 + hstepB, voffB); PG8_STAGE(PG8_SA(0, 0), a2, voffA);
;             PG8_WAIT_V(8); PG8_WAIT_L(0); PG8_BAR; PG8_MMA(1, 0, At, B0); PG8_MMA(1, 1, At, B1); PG8_BAR; PG8_SCHED;
.Ldn_nostg:
	s_or_b32 s44, s56, 1
	s_lshl_b64 s[34:35], s[44:45], 15
	s_sub_u32 s34, 0, s34
	s_subb_u32 s35, 0, s35
	s_add_u32 s44, s28, s34
	s_addc_u32 s65, s29, s35
	s_add_u32 s34, s30, 0xffff8000
	s_addc_u32 s35, s31, -1
	s_add_i32 s66, 0, 0x10000
	v_add_u32_e32 v0, s66, v230
	s_add_i32 s90, 0, 0x14000
	s_waitcnt lgkmcnt(0)
	ds_read_b128 v[130:133], v0
	ds_read_b128 v[134:137], v0 offset:1024
	ds_read_b128 v[138:141], v0 offset:2048
	ds_read_b128 v[142:145], v0 offset:3072
	v_add_u32_e32 v0, s90, v230
	ds_read_b128 v[146:149], v0
	ds_read_b128 v[150:153], v0 offset:1024
	ds_read_b128 v[154:157], v0 offset:2048
	ds_read_b128 v[158:161], v0 offset:3072
	s_add_u32 s88, s44, 0x4000
	s_addc_u32 s89, s65, 0
	s_add_i32 m0, s46, 0xc000
	ds_read_b128 v[162:165], v231
	ds_read_b128 v[166:169], v231 offset:1024
	ds_read_b128 v[170:173], v231 offset:2048
	ds_read_b128 v[174:177], v231 offset:3072
	ds_read_b128 v[178:181], v231 offset:4096
	ds_read_b128 v[182:185], v231 offset:5120
	ds_read_b128 v[186:189], v231 offset:6144
	ds_read_b128 v[190:193], v231 offset:7168
	global_load_lds_dwordx4 v194, s[88:89]
	s_add_i32 m0, s46, 0xe000
	s_nop 0
	global_load_lds_dwordx4 v198, s[88:89]
	s_waitcnt vmcnt(48)
	s_waitcnt lgkmcnt(0)
	s_barrier
	s_setprio 1
	s_waitcnt lgkmcnt(0)
	v_mfma_f32_16x16x32_bf16 v[126:129], v[130:133], v[162:165], 0
	v_mfma_f32_16x16x32_bf16 v[126:129], v[134:137], v[166:169], v[126:129]
	v_mfma_f32_16x16x32_bf16 v[122:125], v[142:145], v[166:169], 0
	v_mfma_f32_16x16x32_bf16 v[122:125], v[138:141], v[162:165], v[122:125]
	v_mfma_f32_16x16x32_bf16 v[106:109], v[138:141], v[170:173], 0
	v_mfma_f32_16x16x32_bf16 v[106:109], v[142:145], v[174:177], v[106:109]
	v_mfma_f32_16x16x32_bf16 v[110:113], v[134:137], v[174:177], 0
	v_mfma_f32_16x16x32_bf16 v[110:113], v[130:133], v[170:173], v[110:113]
	v_mfma_f32_16x16x32_bf16 v[94:97], v[130:133], v[178:181], 0
	v_mfma_f32_16x16x32_bf16 v[94:97], v[134:137], v[182:185], v[94:97]
	v_mfma_f32_16x16x32_bf16 v[90:93], v[142:145], v[182:185], 0
	v_mfma_f32_16x16x32_bf16 v[90:93], v[138:141], v[178:181], v[90:93]
	v_mfma_f32_16x16x32_bf16 v[74:77], v[138:141], v[186:189], 0
	v_mfma_f32_16x16x32_bf16 v[74:77], v[142:145], v[190:193], v[74:77]
	v_mfma_f32_16x16x32_bf16 v[78:81], v[134:137], v[190:193], 0
	v_mfma_f32_16x16x32_bf16 v[78:81], v[130:133], v[186:189], v[78:81]
	s_setprio 0
	s_setprio 1
	v_mfma_f32_16x16x32_bf16 v[118:121], v[146:149], v[162:165], 0
	v_mfma_f32_16x16x32_bf16 v[118:121], v[150:153], v[166:169], v[118:121]
	v_mfma_f32_16x16x32_bf16 v[114:117], v[158:161], v[166:169], 0
	v_mfma_f32_16x16x32_bf16 v[114:117], v[154:157], v[162:165], v[114:117]
	v_mfma_f32_16x16x32_bf16 v[98:101], v[154:157], v[170:173], 0
	v_mfma_f32_16x16x32_bf16 v[98:101], v[158:161], v[174:177], v[98:101]
	v_mfma_f32_16x16x32_bf16 v[102:105], v[150:153], v[174:177], 0
	v_mfma_f32_16x16x32_bf16 v[102:105], v[146:149], v[170:173], v[102:105]
	v_mfma_f32_16x16x32_bf16 v[86:89], v[146:149], v[178:181], 0
	v_mfma_f32_16x16x32_bf16 v[86:89], v[150:153], v[182:185], v[86:89]
	v_mfma_f32_16x16x32_bf16 v[82:85], v[158:161], v[182:185], 0
	v_mfma_f32_16x16x32_bf16 v[82:85], v[154:157], v[178:181], v[82:85]
	v_mfma_f32_16x16x32_bf16 v[66:69], v[154:157], v[186:189], 0
	v_mfma_f32_16x16x32_bf16 v[66:69], v[158:161], v[190:193], v[66:69]
	v_mfma_f32_16x16x32_bf16 v[70:73], v[150:153], v[190:193], 0
	v_mfma_f32_16x16x32_bf16 v[70:73], v[146:149], v[186:189], v[70:73]
	s_setprio 0
	s_barrier
	s_add_i32 s44, s66, s41
	s_mov_b32 m0, s44
	ds_read_b128 v[162:165], v231 offset:16384
	ds_read_b128 v[166:169], v231 offset:17408
	ds_read_b128 v[170:173], v231 offset:18432
	ds_read_b128 v[174:177], v231 offset:19456
	ds_read_b128 v[178:181], v231 offset:20480
	ds_read_b128 v[182:185], v231 offset:21504
	ds_read_b128 v[186:189], v231 offset:22528
	ds_read_b128 v[190:193], v231 offset:23552
	global_load_lds_dwordx4 v196, s[8:9]
	s_add_i32 m0, s44, 0x2000
	s_add_u32 s88, s8, 0x4000
	s_addc_u32 s89, s9, 0
	s_add_i32 s44, s90, s41
	global_load_lds_dwordx4 v200, s[8:9]
	s_mov_b32 m0, s44
	s_nop 0
	global_load_lds_dwordx4 v196, s[88:89]
	s_add_i32 m0, s44, 0x2000
	s_nop 0
	global_load_lds_dwordx4 v200, s[88:89]
	s_mov_b32 m0, s46
	s_nop 0
	global_load_lds_dwordx4 v194, s[30:31]
	s_mov_b32 m0, s47
	s_nop 0
	global_load_lds_dwordx4 v198, s[30:31]
	s_waitcnt vmcnt(48)
	s_waitcnt lgkmcnt(0)
	s_barrier
	s_setprio 1
	s_waitcnt lgkmcnt(0)
	v_mfma_f32_16x16x32_bf16 v[62:65], v[130:133], v[162:165], 0
	v_mfma_f32_16x16x32_bf16 v[62:65], v[134:137], v[166:169], v[62:65]
	v_mfma_f32_16x16x32_bf16 v[58:61], v[142:145], v[166:169], 0
	v_mfma_f32_16x16x32_bf16 v[58:61], v[138:141], v[162:165], v[58:61]
	v_mfma_f32_16x16x32_bf16 v[42:45], v[138:141], v[170:173], 0
	v_mfma_f32_16x16x32_bf16 v[42:45], v[142:145], v[174:177], v[42:45]
	v_mfma_f32_16x16x32_bf16 v[46:49], v[134:137], v[174:177], 0
	v_mfma_f32_16x16x32_bf16 v[46:49], v[130:133], v[170:173], v[46:49]
	v_mfma_f32_16x16x32_bf16 v[30:33], v[130:133], v[178:181], 0
	v_mfma_f32_16x16x32_bf16 v[30:33], v[134:137], v[182:185], v[30:33]
	v_mfma_f32_16x16x32_bf16 v[26:29], v[142:145], v[182:185], 0
	v_mfma_f32_16x16x32_bf16 v[26:29], v[138:141], v[178:181], v[26:29]
	v_mfma_f32_16x16x32_bf16 v[10:13], v[138:141], v[186:189], 0
	v_mfma_f32_16x16x32_bf16 v[10:13], v[142:145], v[190:193], v[10:13]
	v_mfma_f32_16x16x32_bf16 v[14:17], v[134:137], v[190:193], 0
	v_mfma_f32_16x16x32_bf16 v[14:17], v[130:133], v[186:189], v[14:17]
	s_setprio 0
	s_setprio 1
	v_mfma_f32_16x16x32_bf16 v[54:57], v[146:149], v[162:165], 0
	v_mfma_f32_16x16x32_bf16 v[54:57], v[150:153], v[166:169], v[54:57]
	v_mfma_f32_16x16x32_bf16 v[50:53], v[158:161], v[166:169], 0
	v_mfma_f32_16x16x32_bf16 v[50:53], v[154:157], v[162:165], v[50:53]
	v_mfma_f32_16x16x32_bf16 v[34:37], v[154:157], v[170:173], 0
	v_mfma_f32_16x16x32_bf16 v[34:37], v[158:161], v[174:177], v[34:37]
	v_mfma_f32_16x16x32_bf16 v[38:41], v[150:153], v[174:177], 0
	v_mfma_f32_16x16x32_bf16 v[38:41], v[146:149], v[170:173], v[38:41]
	v_mfma_f32_16x16x32_bf16 v[22:25], v[146:149], v[178:181], 0
	v_mfma_f32_16x16x32_bf16 v[22:25], v[150:153], v[182:185], v[22:25]
	v_mfma_f32_16x16x32_bf16 v[18:21], v[158:161], v[182:185], 0
	v_mfma_f32_16x16x32_bf16 v[18:21], v[154:157], v[178:181], v[18:21]
	v_mfma_f32_16x16x32_bf16 v[2:5], v[154:157], v[186:189], 0
	v_mfma_f32_16x16x32_bf16 v[2:5], v[158:161], v[190:193], v[2:5]
	v_mfma_f32_16x16x32_bf16 v[6:9], v[150:153], v[190:193], 0
	v_mfma_f32_16x16x32_bf16 v[6:9], v[146:149], v[186:189], v[6:9]
	s_setprio 0
	s_barrier
	s_branch .Ldn_mid
